# tile index math: group size is provably 8 when nM is a multiple of 8, so the generic integer division (float rcp + fixups) at 18 per-tile sites became a shift
# speedup vs baseline: 1.0012x; 1.0012x over previous
; __device__ __forceinline__ bool tile_of(long Lidx, int nM, int nN, int& pm, int& pn) {
;     ...
;     int wgid = (int)Lidx; { const int q = nwg / NXCD, r = nwg % NXCD, xcd = wgid % NXCD, off = wgid / NXCD; wgid = (xcd < r ? xcd * (q + 1) : r * (q + 1) + (xcd - r) * q) + off; }
;     const int nig = WGM * nN, gid = wgid / nig, fm = gid * WGM, gsz = (nM - fm) < WGM ? (nM - fm) : WGM;
;     pm = fm + ((wgid % nig) % gsz); pn = (wgid % nig) / gsz; return true;
; }
;     __device__ __forceinline__ bool next(int i, Unit& u) const {
;         int pm, pn; if (!tile_of((long)i * G + c, nM, nN, pm, pn)) return false;
;         u.A = A + (size_t)pm * 256 * lda2; u.B = B + (size_t)pn * 256 * ldb2; u.lda2 = lda2; u.ldb2 = ldb2; u.nt = nt; u.kind = 0; u.pm = pm; u.pn = pn; u.z = 0; u.w = 0; return true;
.LBB0_755:
	s_ashr_i32 s30, s54, 3
	s_add_i32 s30, s56, s30
	s_ashr_i32 s31, s30, 31
	s_lshr_b32 s31, s31, 26
	s_add_i32 s31, s30, s31
	s_ashr_i32 s40, s31, 6
	s_lshl_b32 s40, s40, 3
	s_sub_i32 s41, 64, s40
	s_min_i32 s41, s41, 8
	s_andn2_b32 s31, s31, 63
	s_sub_i32 s30, s30, s31
	s_ashr_i32 s54, s30, 3
	s_mul_i32 s31, s54, s41
	s_sub_i32 s30, s30, s31
	s_add_i32 s40, s40, s30
	s_ashr_i32 s41, s40, 31
	s_lshl_b64 s[40:41], s[40:41], 19
	s_add_u32 s40, s4, s40
	s_addc_u32 s41, s5, s41
	s_ashr_i32 s55, s54, 31
	s_lshl_b64 s[54:55], s[54:55], 19
	s_add_u32 s54, s12, s54
	s_addc_u32 s55, s14, s55

; __device__ __forceinline__ bool tile_of(long Lidx, int nM, int nN, int& pm, int& pn) {
;     ...
;     int wgid = (int)Lidx; { const int q = nwg / NXCD, r = nwg % NXCD, xcd = wgid % NXCD, off = wgid / NXCD; wgid = (xcd < r ? xcd * (q + 1) : r * (q + 1) + (xcd - r) * q) + off; }
;     const int nig = WGM * nN, gid = wgid / nig, fm = gid * WGM, gsz = (nM - fm) < WGM ? (nM - fm) : WGM;
;     pm = fm + ((wgid % nig) % gsz); pn = (wgid % nig) / gsz; return true;
.LBB0_765:
	s_ashr_i32 s16, s22, 3
	s_add_i32 s16, s56, s16
	s_ashr_i32 s17, s16, 31
	s_lshr_b32 s17, s17, 26
	s_add_i32 s17, s16, s17
	s_ashr_i32 s22, s17, 6
	s_lshl_b32 s22, s22, 3
	s_sub_i32 s23, 64, s22
	s_min_i32 s23, s23, 8
	s_andn2_b32 s17, s17, 63
	s_sub_i32 s16, s16, s17
	s_ashr_i32 s66, s16, 3
	s_mul_i32 s17, s66, s23
	s_sub_i32 s16, s16, s17
	s_add_i32 s67, s22, s16

; __device__ __forceinline__ bool tile_of(long Lidx, int nM, int nN, int& pm, int& pn) {
;     ...
;     int wgid = (int)Lidx; { const int q = nwg / NXCD, r = nwg % NXCD, xcd = wgid % NXCD, off = wgid / NXCD; wgid = (xcd < r ? xcd * (q + 1) : r * (q + 1) + (xcd - r) * q) + off; }
;     const int nig = WGM * nN, gid = wgid / nig, fm = gid * WGM, gsz = (nM - fm) < WGM ? (nM - fm) : WGM;
;     pm = fm + ((wgid % nig) % gsz); pn = (wgid % nig) / gsz; return true;
; }
;     __device__ __forceinline__ bool next(int i, Unit& u) const {
;         int pm, pn; if (!tile_of((long)i * G + c, nM, nN, pm, pn)) return false;
;         u.A = A + (size_t)pm * 256 * lda2; u.B = B + (size_t)pn * 256 * ldb2; u.lda2 = lda2; u.ldb2 = ldb2; u.nt = nt; u.kind = 0; u.pm = pm; u.pn = pn; u.z = 0; u.w = 0; return true;
.LBB0_979:
	s_ashr_i32 s22, s24, 3
	s_add_i32 s22, s40, s22
	s_ashr_i32 s23, s22, 31
	s_lshr_b32 s23, s23, 26
	s_add_i32 s23, s22, s23
	s_ashr_i32 s24, s23, 6
	s_lshl_b32 s25, s24, 3
	s_sub_i32 s24, 0x80, s25
	s_min_i32 s30, s24, 8
	s_andn2_b32 s23, s23, 63
	s_sub_i32 s22, s22, s23
	s_ashr_i32 s24, s22, 3
	s_mul_i32 s23, s24, s30
	s_sub_i32 s22, s22, s23
	s_add_i32 s22, s25, s22
	s_ashr_i32 s23, s22, 31
	s_lshl_b64 s[22:23], s[22:23], 19
	s_add_u32 s22, s4, s22
	s_addc_u32 s23, s5, s23
	s_ashr_i32 s25, s24, 31
	s_lshl_b64 s[24:25], s[24:25], 19
	s_add_u32 s24, s31, s24
	s_addc_u32 s25, s33, s25

; __device__ __forceinline__ bool tile_of(long Lidx, int nM, int nN, int& pm, int& pn) {
;     ...
;     int wgid = (int)Lidx; { const int q = nwg / NXCD, r = nwg % NXCD, xcd = wgid % NXCD, off = wgid / NXCD; wgid = (xcd < r ? xcd * (q + 1) : r * (q + 1) + (xcd - r) * q) + off; }
;     const int nig = WGM * nN, gid = wgid / nig, fm = gid * WGM, gsz = (nM - fm) < WGM ? (nM - fm) : WGM;
;     pm = fm + ((wgid % nig) % gsz); pn = (wgid % nig) / gsz; return true;
.LBB0_989:
	s_ashr_i32 s20, s26, 3
	s_add_i32 s20, s38, s20
	s_ashr_i32 s21, s20, 31
	s_lshr_b32 s21, s21, 26
	s_add_i32 s21, s20, s21
	s_ashr_i32 s26, s21, 6
	s_lshl_b32 s26, s26, 3
	s_sub_i32 s27, 0x80, s26
	s_min_i32 s27, s27, 8
	s_andn2_b32 s21, s21, 63
	s_sub_i32 s20, s20, s21
	s_ashr_i32 s61, s20, 3
	s_mul_i32 s21, s61, s27
	s_sub_i32 s20, s20, s21
	s_add_i32 s20, s26, s20

; __device__ __forceinline__ bool tile_of(long Lidx, int nM, int nN, int& pm, int& pn) {
;     ...
;     int wgid = (int)Lidx; { const int q = nwg / NXCD, r = nwg % NXCD, xcd = wgid % NXCD, off = wgid / NXCD; wgid = (xcd < r ? xcd * (q + 1) : r * (q + 1) + (xcd - r) * q) + off; }
;     const int nig = WGM * nN, gid = wgid / nig, fm = gid * WGM, gsz = (nM - fm) < WGM ? (nM - fm) : WGM;
;     pm = fm + ((wgid % nig) % gsz); pn = (wgid % nig) / gsz; return true;
.LBB0_1019:
	s_ashr_i32 s20, s26, 3
	s_add_i32 s20, s38, s20
	s_ashr_i32 s21, s20, 31
	s_lshr_b32 s21, s21, 26
	s_add_i32 s21, s20, s21
	s_ashr_i32 s26, s21, 6
	s_lshl_b32 s26, s26, 3
	s_sub_i32 s27, 0x80, s26
	s_min_i32 s27, s27, 8
	s_andn2_b32 s21, s21, 63
	s_sub_i32 s20, s20, s21
	s_ashr_i32 s60, s20, 3
	s_mul_i32 s21, s60, s27
	s_sub_i32 s20, s20, s21
	s_add_i32 s20, s26, s20

; __device__ __forceinline__ bool tile_of(long Lidx, int nM, int nN, int& pm, int& pn) {
;     ...
;     int wgid = (int)Lidx; { const int q = nwg / NXCD, r = nwg % NXCD, xcd = wgid % NXCD, off = wgid / NXCD; wgid = (xcd < r ? xcd * (q + 1) : r * (q + 1) + (xcd - r) * q) + off; }
;     const int nig = WGM * nN, gid = wgid / nig, fm = gid * WGM, gsz = (nM - fm) < WGM ? (nM - fm) : WGM;
;     pm = fm + ((wgid % nig) % gsz); pn = (wgid % nig) / gsz; return true;
; }
;     __device__ __forceinline__ bool next(int i, Unit& u) const {
;         int pm, pn; if (!tile_of((long)i * G + c, nM, nN, pm, pn)) return false;
;         u.A = A + (size_t)pm * 256 * lda2; u.B = B + (size_t)pn * 256 * ldb2; u.lda2 = lda2; u.ldb2 = ldb2; u.nt = nt; u.kind = 0; u.pm = pm; u.pn = pn; u.z = 0; u.w = 0; return true;
.LBB0_1087:
	s_ashr_i32 s24, s26, 3
	s_add_i32 s24, s42, s24
	s_ashr_i32 s25, s24, 31
	s_lshr_b32 s25, s25, 27
	s_add_i32 s25, s24, s25
	s_ashr_i32 s26, s25, 5
	s_lshl_b32 s27, s26, 3
	s_sub_i32 s26, 0x80, s27
	s_min_i32 s30, s26, 8
	s_andn2_b32 s25, s25, 31
	s_sub_i32 s24, s24, s25
	s_ashr_i32 s26, s24, 3
	s_mul_i32 s25, s26, s30
	s_sub_i32 s24, s24, s25
	s_add_i32 s24, s27, s24
	s_ashr_i32 s25, s24, 31
	s_lshl_b64 s[24:25], s[24:25], 20
	s_add_u32 s24, s12, s24
	s_addc_u32 s25, s13, s25
	s_ashr_i32 s27, s26, 31
	s_lshl_b64 s[26:27], s[26:27], 20
	s_add_u32 s26, s4, s26
	s_addc_u32 s27, s5, s27

; __device__ __forceinline__ bool tile_of(long Lidx, int nM, int nN, int& pm, int& pn) {
;     ...
;     int wgid = (int)Lidx; { const int q = nwg / NXCD, r = nwg % NXCD, xcd = wgid % NXCD, off = wgid / NXCD; wgid = (xcd < r ? xcd * (q + 1) : r * (q + 1) + (xcd - r) * q) + off; }
;     const int nig = WGM * nN, gid = wgid / nig, fm = gid * WGM, gsz = (nM - fm) < WGM ? (nM - fm) : WGM;
;     pm = fm + ((wgid % nig) % gsz); pn = (wgid % nig) / gsz; return true;
.LBB0_1097:
	s_ashr_i32 s22, s38, 3
	s_add_i32 s22, s40, s22
	s_ashr_i32 s23, s22, 31
	s_lshr_b32 s23, s23, 27
	s_add_i32 s23, s22, s23
	s_ashr_i32 s30, s23, 5
	s_lshl_b32 s30, s30, 3
	s_sub_i32 s38, 0x80, s30
	s_min_i32 s38, s38, 8
	s_andn2_b32 s23, s23, 31
	s_sub_i32 s22, s22, s23
	s_ashr_i32 s59, s22, 3
	s_mul_i32 s23, s59, s38
	s_sub_i32 s22, s22, s23
	s_add_i32 s22, s30, s22

; __device__ __forceinline__ bool tile_of(long Lidx, int nM, int nN, int& pm, int& pn) {
;     ...
;     int wgid = (int)Lidx; { const int q = nwg / NXCD, r = nwg % NXCD, xcd = wgid % NXCD, off = wgid / NXCD; wgid = (xcd < r ? xcd * (q + 1) : r * (q + 1) + (xcd - r) * q) + off; }
;     const int nig = WGM * nN, gid = wgid / nig, fm = gid * WGM, gsz = (nM - fm) < WGM ? (nM - fm) : WGM;
;     pm = fm + ((wgid % nig) % gsz); pn = (wgid % nig) / gsz; return true;
; }
;     __device__ __forceinline__ bool next(int i, Unit& u) const {
;         int pm, pn; if (!tile_of((long)i * G + c, nM, nN, pm, pn)) return false;
;         u.A = A + (size_t)pm * 256 * lda2; u.B = B + (size_t)pn * 256 * ldb2; u.lda2 = lda2; u.ldb2 = ldb2; u.nt = nt; u.kind = 0; u.pm = pm; u.pn = pn; u.z = 0; u.w = 0; return true;
.LBB0_1190:
	s_ashr_i32 s20, s22, 3
	s_add_i32 s20, s38, s20
	s_ashr_i32 s21, s20, 31
	s_lshr_b32 s21, s21, 27
	s_add_i32 s21, s20, s21
	s_ashr_i32 s22, s21, 5
	s_lshl_b32 s23, s22, 3
	s_sub_i32 s22, 0x80, s23
	s_min_i32 s30, s22, 8
	s_andn2_b32 s21, s21, 31
	s_sub_i32 s20, s20, s21
	s_ashr_i32 s22, s20, 3
	s_mul_i32 s21, s22, s30
	s_sub_i32 s20, s20, s21
	s_add_i32 s20, s23, s20
	s_ashr_i32 s21, s20, 31
	s_lshl_b64 s[20:21], s[20:21], 19
	s_add_u32 s20, s4, s20
	s_addc_u32 s21, s5, s21
	s_ashr_i32 s23, s22, 31
	s_lshl_b64 s[22:23], s[22:23], 19
	s_add_u32 s22, s31, s22
	s_addc_u32 s23, s33, s23

; __device__ __forceinline__ bool tile_of(long Lidx, int nM, int nN, int& pm, int& pn) {
;     ...
;     int wgid = (int)Lidx; { const int q = nwg / NXCD, r = nwg % NXCD, xcd = wgid % NXCD, off = wgid / NXCD; wgid = (xcd < r ? xcd * (q + 1) : r * (q + 1) + (xcd - r) * q) + off; }
;     const int nig = WGM * nN, gid = wgid / nig, fm = gid * WGM, gsz = (nM - fm) < WGM ? (nM - fm) : WGM;
;     pm = fm + ((wgid % nig) % gsz); pn = (wgid % nig) / gsz; return true;
.LBB0_1200:
	s_ashr_i32 s18, s24, 3
	s_add_i32 s18, s26, s18
	s_ashr_i32 s19, s18, 31
	s_lshr_b32 s19, s19, 27
	s_add_i32 s19, s18, s19
	s_ashr_i32 s24, s19, 5
	s_lshl_b32 s24, s24, 3
	s_sub_i32 s25, 0x80, s24
	s_min_i32 s25, s25, 8
	s_andn2_b32 s19, s19, 31
	s_sub_i32 s18, s18, s19
	s_ashr_i32 s57, s18, 3
	s_mul_i32 s19, s57, s25
	s_sub_i32 s18, s18, s19
	s_add_i32 s18, s24, s18

; __device__ __forceinline__ bool tile_of(long Lidx, int nM, int nN, int& pm, int& pn) {
;     ...
;     int wgid = (int)Lidx; { const int q = nwg / NXCD, r = nwg % NXCD, xcd = wgid % NXCD, off = wgid / NXCD; wgid = (xcd < r ? xcd * (q + 1) : r * (q + 1) + (xcd - r) * q) + off; }
;     const int nig = WGM * nN, gid = wgid / nig, fm = gid * WGM, gsz = (nM - fm) < WGM ? (nM - fm) : WGM;
;     pm = fm + ((wgid % nig) % gsz); pn = (wgid % nig) / gsz; return true;
; }
;     __device__ __forceinline__ bool next(int i, Unit& u) const {
;         int pm, pn; if (!tile_of((long)i * G + c, nM, nN, pm, pn)) return false;
;         u.A = A + (size_t)pm * 256 * lda2; u.B = B + (size_t)pn * 256 * ldb2; u.lda2 = lda2; u.ldb2 = ldb2; u.nt = nt; u.kind = 0; u.pm = pm; u.pn = pn; u.z = 0; u.w = 0; return true;
.LBB0_1272:
	s_ashr_i32 s24, s26, 3
	s_add_i32 s24, s42, s24
	s_ashr_i32 s25, s24, 31
	s_lshr_b32 s25, s25, 26
	s_add_i32 s25, s24, s25
	s_ashr_i32 s26, s25, 6
	s_lshl_b32 s27, s26, 3
	s_sub_i32 s26, 0x80, s27
	s_min_i32 s30, s26, 8
	s_andn2_b32 s25, s25, 63
	s_sub_i32 s24, s24, s25
	s_ashr_i32 s26, s24, 3
	s_mul_i32 s25, s26, s30
	s_sub_i32 s24, s24, s25
	s_add_i32 s24, s27, s24
	s_ashr_i32 s25, s24, 31
	s_lshl_b64 s[24:25], s[24:25], 19
	s_add_u32 s24, s4, s24
	s_addc_u32 s25, s5, s25
	s_ashr_i32 s27, s26, 31
	s_lshl_b64 s[26:27], s[26:27], 19
	s_add_u32 s26, s31, s26
	s_addc_u32 s27, s33, s27

; __device__ __forceinline__ bool tile_of(long Lidx, int nM, int nN, int& pm, int& pn) {
;     ...
;     int wgid = (int)Lidx; { const int q = nwg / NXCD, r = nwg % NXCD, xcd = wgid % NXCD, off = wgid / NXCD; wgid = (xcd < r ? xcd * (q + 1) : r * (q + 1) + (xcd - r) * q) + off; }
;     const int nig = WGM * nN, gid = wgid / nig, fm = gid * WGM, gsz = (nM - fm) < WGM ? (nM - fm) : WGM;
;     pm = fm + ((wgid % nig) % gsz); pn = (wgid % nig) / gsz; return true;
.LBB0_1282:
	s_ashr_i32 s22, s38, 3
	s_add_i32 s22, s40, s22
	s_ashr_i32 s23, s22, 31
	s_lshr_b32 s23, s23, 26
	s_add_i32 s23, s22, s23
	s_ashr_i32 s30, s23, 6
	s_lshl_b32 s30, s30, 3
	s_sub_i32 s38, 0x80, s30
	s_min_i32 s38, s38, 8
	s_andn2_b32 s23, s23, 63
	s_sub_i32 s22, s22, s23
	s_ashr_i32 s60, s22, 3
	s_mul_i32 s23, s60, s38
	s_sub_i32 s22, s22, s23
	s_add_i32 s22, s30, s22

; __device__ __forceinline__ bool tile_of(long Lidx, int nM, int nN, int& pm, int& pn) {
;     ...
;     int wgid = (int)Lidx; { const int q = nwg / NXCD, r = nwg % NXCD, xcd = wgid % NXCD, off = wgid / NXCD; wgid = (xcd < r ? xcd * (q + 1) : r * (q + 1) + (xcd - r) * q) + off; }
;     const int nig = WGM * nN, gid = wgid / nig, fm = gid * WGM, gsz = (nM - fm) < WGM ? (nM - fm) : WGM;
;     pm = fm + ((wgid % nig) % gsz); pn = (wgid % nig) / gsz; return true;
; }
;     __device__ __forceinline__ bool next(int i, Unit& u) const {
;         int pm, pn; if (!tile_of((long)i * G + c, nM, nN, pm, pn)) return false;
;         u.A = A + (size_t)pm * 256 * lda2; u.B = B + (size_t)pn * 256 * ldb2; u.lda2 = lda2; u.ldb2 = ldb2; u.nt = nt; u.kind = 0; u.pm = pm; u.pn = pn; u.z = 0; u.w = 0; return true;
.LBB0_1350:
	s_ashr_i32 s18, s20, 3
	s_add_i32 s18, s26, s18
	s_ashr_i32 s19, s18, 31
	s_lshr_b32 s19, s19, 27
	s_add_i32 s19, s18, s19
	s_ashr_i32 s20, s19, 5
	s_lshl_b32 s21, s20, 3
	s_sub_i32 s20, 0x80, s21
	s_min_i32 s26, s20, 8
	s_andn2_b32 s19, s19, 31
	s_sub_i32 s18, s18, s19
	s_ashr_i32 s20, s18, 3
	s_mul_i32 s19, s20, s26
	s_sub_i32 s18, s18, s19
	s_add_i32 s18, s21, s18
	s_ashr_i32 s19, s18, 31
	s_lshl_b64 s[18:19], s[18:19], 19
	s_add_u32 s18, s4, s18
	s_addc_u32 s19, s5, s19
	s_ashr_i32 s21, s20, 31
	s_lshl_b64 s[20:21], s[20:21], 19
	s_add_u32 s20, s31, s20
	s_addc_u32 s21, s33, s21

; __device__ __forceinline__ bool tile_of(long Lidx, int nM, int nN, int& pm, int& pn) {
;     ...
;     int wgid = (int)Lidx; { const int q = nwg / NXCD, r = nwg % NXCD, xcd = wgid % NXCD, off = wgid / NXCD; wgid = (xcd < r ? xcd * (q + 1) : r * (q + 1) + (xcd - r) * q) + off; }
;     const int nig = WGM * nN, gid = wgid / nig, fm = gid * WGM, gsz = (nM - fm) < WGM ? (nM - fm) : WGM;
;     pm = fm + ((wgid % nig) % gsz); pn = (wgid % nig) / gsz; return true;
.LBB0_1360:
	s_ashr_i32 s16, s22, 3
	s_add_i32 s16, s24, s16
	s_ashr_i32 s17, s16, 31
	s_lshr_b32 s17, s17, 27
	s_add_i32 s17, s16, s17
	s_ashr_i32 s22, s17, 5
	s_lshl_b32 s22, s22, 3
	s_sub_i32 s23, 0x80, s22
	s_min_i32 s23, s23, 8
	s_andn2_b32 s17, s17, 31
	s_sub_i32 s16, s16, s17
	s_ashr_i32 s58, s16, 3
	s_mul_i32 s17, s58, s23
	s_sub_i32 s16, s16, s17
	s_add_i32 s16, s22, s16

; __device__ __forceinline__ bool tile_of(long Lidx, int nM, int nN, int& pm, int& pn) {
;     const int nwg = nM * nN; if (Lidx >= nwg) return false;
;     int wgid = (int)Lidx; { const int q = nwg / NXCD, r = nwg % NXCD, xcd = wgid % NXCD, off = wgid / NXCD; wgid = (xcd < r ? xcd * (q + 1) : r * (q + 1) + (xcd - r) * q) + off; }
;     const int nig = WGM * nN, gid = wgid / nig, fm = gid * WGM, gsz = (nM - fm) < WGM ? (nM - fm) : WGM;
;     pm = fm + ((wgid % nig) % gsz); pn = (wgid % nig) / gsz; return true;
; }
;     __device__ __forceinline__ bool next(int i, Unit& u) const {
;         int pm, pn; if (!tile_of((long)i * G + c, nM, nN, pm, pn)) return false;
;         u.A = A + (size_t)pm * 256 * lda2; u.B = B + (size_t)pn * 256 * ldb2; u.lda2 = lda2; u.ldb2 = ldb2; u.nt = nt; u.kind = 0; u.pm = pm; u.pn = pn; u.z = 0; u.w = 0; return true;
.LBB0_1482:
	s_add_i32 s57, s19, 1
	s_mul_i32 s8, s57, s29
	s_mul_hi_u32 s9, s57, s28
	s_add_i32 s9, s9, s8
	s_mul_i32 s8, s57, s28
	s_add_u32 s38, s8, s2
	s_addc_u32 s39, s9, s3
	v_cmp_gt_i64_e32 vcc, s[38:39], v[130:131]
	v_cmp_lt_i64_e64 s[8:9], s[38:39], v[128:129]
	s_cbranch_vccnz .LBB0_1484
	s_ashr_i32 s20, s38, 31
	s_lshr_b32 s20, s20, 29
	s_add_i32 s20, s38, s20
	s_ashr_i32 s21, s20, 3
	s_and_b32 s20, s20, -8
	s_sub_i32 s20, s38, s20
	s_cmp_lt_i32 s20, 0
	s_cselect_b32 s22, s35, 0x160
	s_mul_i32 s20, s20, s22
	s_add_i32 s20, s20, s21
	s_mul_hi_i32 s21, s20, 0x2e8ba2e9
	s_lshr_b32 s22, s21, 31
	s_ashr_i32 s21, s21, 5
	s_add_i32 s21, s21, s22
	s_lshl_b32 s23, s21, 3
	s_sub_i32 s22, 0x80, s23
	s_min_i32 s30, s22, 8
	s_mulk_i32 s21, 0xb0
	s_sub_i32 s20, s20, s21
	s_ashr_i32 s22, s20, 3
	s_mul_i32 s21, s22, s30
	s_sub_i32 s20, s20, s21
	s_add_i32 s20, s23, s20
	s_ashr_i32 s21, s20, 31
	s_lshl_b64 s[20:21], s[20:21], 19
	s_add_u32 s20, s4, s20
	s_addc_u32 s21, s5, s21
	s_ashr_i32 s23, s22, 31
	s_lshl_b64 s[22:23], s[22:23], 19
	s_add_u32 s22, s31, s22
	s_addc_u32 s23, s33, s23

; __device__ __forceinline__ bool tile_of(long Lidx, int nM, int nN, int& pm, int& pn) {
;     const int nwg = nM * nN; if (Lidx >= nwg) return false;
;     int wgid = (int)Lidx; { const int q = nwg / NXCD, r = nwg % NXCD, xcd = wgid % NXCD, off = wgid / NXCD; wgid = (xcd < r ? xcd * (q + 1) : r * (q + 1) + (xcd - r) * q) + off; }
;     const int nig = WGM * nN, gid = wgid / nig, fm = gid * WGM, gsz = (nM - fm) < WGM ? (nM - fm) : WGM;
;     pm = fm + ((wgid % nig) % gsz); pn = (wgid % nig) / gsz; return true;
;     __device__ __forceinline__ bool next(int i, Unit& u) const {
;         int pm, pn; if (!tile_of((long)i * G + c, nM, nN, pm, pn)) return false;
;         u.A = A + (size_t)pm * 256 * lda2; u.B = B + (size_t)pn * 256 * ldb2; u.lda2 = lda2; u.ldb2 = ldb2; u.nt = nt; u.kind = 0; u.pm = pm; u.pn = pn; u.z = 0; u.w = 0; return true;
.LBB0_1488:
	v_mov_b32_e32 v133, v137
	v_mov_b32_e32 v132, v136
	v_mov_b32_e32 v143, s28
	v_mov_b64_e32 v[144:145], s[2:3]
	s_nop 0
	v_mad_i64_i32 v[144:145], s[24:25], s19, v143, v[144:145]
	v_cmp_lt_i64_e32 vcc, s[16:17], v[144:145]
	v_readfirstlane_b32 s19, v144
	s_cbranch_vccnz .LBB0_1490
	s_ashr_i32 s18, s19, 31
	s_lshr_b32 s18, s18, 29
	s_add_i32 s18, s19, s18
	s_ashr_i32 s24, s18, 3
	s_and_b32 s18, s18, -8
	s_sub_i32 s18, s19, s18
	s_cmp_lt_i32 s18, 0
	s_cselect_b32 s19, s35, 0x160
	s_mul_i32 s18, s18, s19
	s_add_i32 s18, s18, s24
	s_mul_hi_i32 s19, s18, 0x2e8ba2e9
	s_lshr_b32 s24, s19, 31
	s_ashr_i32 s19, s19, 5
	s_add_i32 s19, s19, s24
	s_lshl_b32 s24, s19, 3
	s_sub_i32 s25, 0x80, s24
	s_min_i32 s25, s25, 8
	s_mulk_i32 s19, 0xb0
	s_sub_i32 s18, s18, s19
	s_ashr_i32 s58, s18, 3
	s_mul_i32 s19, s58, s25
	s_sub_i32 s18, s18, s19
	s_add_i32 s18, s24, s18

; __device__ __forceinline__ bool tile_of(long Lidx, int nM, int nN, int& pm, int& pn) {
;     ...
;     int wgid = (int)Lidx; { const int q = nwg / NXCD, r = nwg % NXCD, xcd = wgid % NXCD, off = wgid / NXCD; wgid = (xcd < r ? xcd * (q + 1) : r * (q + 1) + (xcd - r) * q) + off; }
;     const int nig = WGM * nN, gid = wgid / nig, fm = gid * WGM, gsz = (nM - fm) < WGM ? (nM - fm) : WGM;
;     pm = fm + ((wgid % nig) % gsz); pn = (wgid % nig) / gsz; return true;
; }
;     __device__ __forceinline__ bool next(int i, Unit& u) const {
;         int pm, pn; if (!tile_of((long)i * G + c, nM, nN, pm, pn)) return false;
;         u.A = A + (size_t)pm * 256 * lda2; u.B = B + (size_t)pn * 256 * ldb2; u.lda2 = lda2; u.ldb2 = ldb2; u.nt = nt; u.kind = 0; u.pm = pm; u.pn = pn; u.z = 0; u.w = 0; return true;
.LBB0_1557:
	s_ashr_i32 s18, s20, 3
	s_add_i32 s18, s26, s18
	s_ashr_i32 s19, s18, 31
	s_lshr_b32 s19, s19, 27
	s_add_i32 s19, s18, s19
	s_ashr_i32 s20, s19, 5
	s_lshl_b32 s20, s20, 3
	s_sub_i32 s21, 0x80, s20
	s_min_i32 s21, s21, 8
	s_andn2_b32 s19, s19, 31
	s_sub_i32 s18, s18, s19
	s_ashr_i32 s26, s18, 3
	s_mul_i32 s19, s26, s21
	s_sub_i32 s18, s18, s19
	s_add_i32 s18, s20, s18
	s_mul_hi_i32 s19, s18, 0x160000
	s_mul_i32 s18, s18, 0x160000
	s_add_u32 s18, s4, s18
	s_addc_u32 s19, s5, s19
	s_mul_hi_i32 s21, s26, 0x160000
	s_mul_i32 s26, s26, 0x160000
	s_add_u32 s20, s31, s26
	s_addc_u32 s21, s33, s21
